# attention main loops: one workgroup barrier per KV tile instead of two (K writes ahead of the barrier, V write after it)
# baseline (speedup 1.0000x reference)
.LBB0_716:
	s_waitcnt vmcnt(3)
	ds_write_b128 v173, v[124:127] offset:16384
	ds_write_b128 v174, v[128:131] offset:16384
	s_waitcnt lgkmcnt(0)
	s_barrier
	v_cmp_gt_f32_e32 vcc, 1.0, v181
	ds_write_b128 v176, v[120:123]
	s_cbranch_vccz .LBB0_720
	s_and_saveexec_b64 s[2:3], s[40:41]
	ds_write_b32 v164, v181 offset:49280
	s_or_b64 exec, exec, s[2:3]
	s_waitcnt lgkmcnt(0)
	v_add_u32_e32 v60, v163, v188
	ds_read_b128 v[48:51], v60 offset:49376
	ds_read_b128 v[52:55], v60 offset:49344
	ds_read_b128 v[56:59], v60 offset:49312
	ds_read_b128 v[60:63], v60 offset:49280
	s_waitcnt lgkmcnt(3)
	v_pk_mul_f32 v[28:29], v[28:29], v[48:49]
	s_waitcnt lgkmcnt(2)
	v_pk_mul_f32 v[24:25], v[24:25], v[52:53]
	s_waitcnt lgkmcnt(1)
	v_pk_mul_f32 v[20:21], v[20:21], v[56:57]
	v_pk_mul_f32 v[30:31], v[30:31], v[50:51]
	v_pk_mul_f32 v[26:27], v[26:27], v[54:55]
	v_pk_mul_f32 v[22:23], v[22:23], v[58:59]
	s_waitcnt lgkmcnt(0)
	v_pk_mul_f32 v[18:19], v[18:19], v[62:63]
	v_pk_mul_f32 v[16:17], v[16:17], v[60:61]
	v_pk_mul_f32 v[12:13], v[12:13], v[48:49]
	v_pk_mul_f32 v[8:9], v[8:9], v[52:53]
	v_pk_mul_f32 v[4:5], v[4:5], v[56:57]
	v_pk_mul_f32 v[14:15], v[14:15], v[50:51]
	v_pk_mul_f32 v[10:11], v[10:11], v[54:55]
	v_pk_mul_f32 v[6:7], v[6:7], v[58:59]
	v_pk_mul_f32 v[2:3], v[2:3], v[62:63]
	v_pk_mul_f32 v[0:1], v[0:1], v[60:61]
.LBB0_720:
	v_exp_f32_e32 v131, v82
	v_exp_f32_e32 v129, v84
	v_exp_f32_e32 v128, v86
	v_exp_f32_e32 v130, v87
	v_exp_f32_e32 v125, v88
	v_exp_f32_e32 v127, v89
	v_exp_f32_e32 v123, v90
	v_exp_f32_e32 v126, v91
	v_exp_f32_e32 v121, v92
	v_exp_f32_e32 v124, v93
	v_exp_f32_e32 v120, v94
	v_exp_f32_e32 v122, v95
	v_exp_f32_e32 v183, v80
	v_exp_f32_e32 v185, v81
	v_exp_f32_e32 v184, v83
	v_exp_f32_e32 v182, v85
	s_waitcnt lgkmcnt(0)
	ds_read_b128 v[48:51], v166 offset:16384
	ds_read_b128 v[200:203], v166 offset:24576
	v_exp_f32_e32 v186, v64
	v_add_f32_e32 v64, 0, v183
	v_add_f32_e32 v64, v185, v64
	s_waitcnt lgkmcnt(1)
	v_mfma_f32_32x32x16_bf16 v[80:95], v[48:51], v[116:119], v[32:47]
	v_add_f32_e32 v64, v131, v64
	v_add_f32_e32 v64, v184, v64
	v_add_f32_e32 v64, v129, v64
	v_add_f32_e32 v64, v182, v64
	v_add_f32_e32 v64, v128, v64
	v_add_f32_e32 v64, v130, v64
	v_add_f32_e32 v64, v125, v64
	s_waitcnt lgkmcnt(0)
	v_mfma_f32_32x32x16_bf16 v[48:63], v[200:203], v[116:119], v[32:47]
	ds_read_b128 v[200:203], v167 offset:16384
	ds_read_b128 v[204:207], v167 offset:24576
	v_add_f32_e32 v64, v127, v64
	v_add_f32_e32 v64, v123, v64
	v_add_f32_e32 v64, v126, v64
	v_add_f32_e32 v64, v121, v64
	v_exp_f32_e32 v187, v65
	v_add_f32_e32 v64, v124, v64
	s_waitcnt lgkmcnt(1)
	v_mfma_f32_32x32x16_bf16 v[80:95], v[200:203], v[112:115], v[80:95]
	v_exp_f32_e32 v196, v66
	v_add_f32_e32 v64, v120, v64
	v_exp_f32_e32 v197, v67
	v_add_f32_e32 v64, v122, v64
	v_add_f32_e32 v64, v186, v64
	v_add_f32_e32 v64, v187, v64
	v_add_f32_e32 v64, v196, v64
	s_waitcnt lgkmcnt(0)
	v_mfma_f32_32x32x16_bf16 v[48:63], v[204:207], v[112:115], v[48:63]
	ds_read_b128 v[200:203], v169 offset:16384
	ds_read_b128 v[204:207], v169 offset:24576
	v_add_f32_e32 v64, v197, v64
	v_exp_f32_e32 v208, v76
	v_exp_f32_e32 v209, v77
	v_exp_f32_e32 v78, v78
	v_exp_f32_e32 v79, v79
	s_waitcnt lgkmcnt(1)
	v_mfma_f32_32x32x16_bf16 v[80:95], v[200:203], v[108:111], v[80:95]
	s_waitcnt lgkmcnt(0)
	v_mfma_f32_32x32x16_bf16 v[48:63], v[204:207], v[108:111], v[48:63]
	ds_read_b128 v[200:203], v170 offset:16384
	ds_read_b128 v[204:207], v170 offset:24576
	s_waitcnt lgkmcnt(1)
	v_mfma_f32_32x32x16_bf16 v[80:95], v[200:203], v[104:107], v[80:95]
	s_waitcnt lgkmcnt(0)
	v_mfma_f32_32x32x16_bf16 v[48:63], v[204:207], v[104:107], v[48:63]
	ds_read_b128 v[200:203], v168 offset:16384
	ds_read_b128 v[204:207], v168 offset:24576
	s_waitcnt lgkmcnt(1)
	v_mfma_f32_32x32x16_bf16 v[80:95], v[200:203], v[100:103], v[80:95]
	s_waitcnt lgkmcnt(0)
	v_mfma_f32_32x32x16_bf16 v[48:63], v[204:207], v[100:103], v[48:63]
	ds_read_b128 v[200:203], v171 offset:16384
	ds_read_b128 v[204:207], v171 offset:24576
	v_cvt_pk_bf16_f32 v66, v183, v185
	v_cvt_pk_bf16_f32 v67, v131, v184
	s_waitcnt lgkmcnt(1)
	v_mfma_f32_32x32x16_bf16 v[80:95], v[200:203], v[96:99], v[80:95]
	v_exp_f32_e32 v200, v68
	v_exp_f32_e32 v201, v69
	v_exp_f32_e32 v202, v70
	v_exp_f32_e32 v203, v71
	v_add_f32_e32 v64, v200, v64
	v_add_f32_e32 v64, v201, v64
	v_add_f32_e32 v64, v202, v64
	s_waitcnt lgkmcnt(0)
	v_mfma_f32_32x32x16_bf16 v[48:63], v[204:207], v[96:99], v[48:63]
	v_exp_f32_e32 v204, v72
	v_exp_f32_e32 v205, v73
	v_exp_f32_e32 v206, v74
	v_exp_f32_e32 v207, v75
	v_add_f32_e32 v64, v203, v64
	v_add_f32_e32 v64, v204, v64
	v_add_f32_e32 v64, v205, v64
	v_add_f32_e32 v64, v206, v64
	v_add_f32_e32 v64, v207, v64
	v_add_f32_e32 v64, v208, v64
	v_add_f32_e32 v64, v209, v64
	v_add_f32_e32 v64, v78, v64
	v_add_f32_e32 v64, v79, v64
	v_mov_b32_e32 v65, v64
	v_cvt_pk_bf16_f32 v68, v129, v182
	v_cvt_pk_bf16_f32 v69, v128, v130
	s_nop 1
	v_permlane32_swap_b32_e32 v64, v65
	v_permlane32_swap_b32_e32 v66, v68
	v_permlane32_swap_b32_e32 v67, v69
	v_cvt_pk_bf16_f32 v70, v125, v127
	v_cvt_pk_bf16_f32 v71, v123, v126
	v_cvt_pk_bf16_f32 v72, v121, v124
	v_cvt_pk_bf16_f32 v73, v120, v122
	v_cvt_pk_bf16_f32 v74, v186, v187
	v_cvt_pk_bf16_f32 v75, v196, v197
	v_cvt_pk_bf16_f32 v76, v200, v201
	v_cvt_pk_bf16_f32 v77, v202, v203
	v_cvt_pk_bf16_f32 v182, v204, v205
	v_cvt_pk_bf16_f32 v183, v206, v207
	v_cvt_pk_bf16_f32 v184, v208, v209
	v_cvt_pk_bf16_f32 v185, v78, v79
	s_nop 0
	v_permlane32_swap_b32_e32 v70, v72
	v_permlane32_swap_b32_e32 v71, v73
	v_permlane32_swap_b32_e32 v74, v76
	v_permlane32_swap_b32_e32 v75, v77
	v_permlane32_swap_b32_e32 v182, v184
	v_permlane32_swap_b32_e32 v183, v185
	s_add_i32 s2, s59, -2
	s_min_u32 s2, s2, s58
	s_lshl_b32 s2, s2, 6
	v_add_u32_e32 v78, s2, v148
	v_ashrrev_i32_e32 v79, 31, v78
	v_lshlrev_b64 v[78:79], 7, v[78:79]
	v_lshl_add_u64 v[78:79], v[152:153], 0, v[78:79]
	global_load_dwordx4 v[120:123], v[78:79], off
	v_add_u32_e32 v78, s2, v146
	v_add_u32_e32 v124, s2, v150
	v_ashrrev_i32_e32 v79, 31, v78
	v_ashrrev_i32_e32 v125, 31, v124
	v_lshlrev_b64 v[78:79], v172, v[78:79]
	v_lshlrev_b64 v[124:125], v172, v[124:125]
	v_lshl_add_u64 v[78:79], v[78:79], 1, v[144:145]
	v_lshl_add_u64 v[128:129], v[124:125], 1, v[144:145]
	global_load_dwordx4 v[124:127], v[78:79], off
	s_nop 0
	global_load_dwordx4 v[128:131], v[128:129], off
	ds_read_b64_tr_b16 v[200:201], v157 offset:0
	ds_read_b64_tr_b16 v[202:203], v157 offset:0x400
	ds_read_b64_tr_b16 v[204:205], v157 offset:0x800
	ds_read_b64_tr_b16 v[206:207], v157 offset:0xc00
	ds_read_b64_tr_b16 v[208:209], v157 offset:0x1000
	ds_read_b64_tr_b16 v[210:211], v157 offset:0x1400
	ds_read_b64_tr_b16 v[212:213], v157 offset:0x1800
	ds_read_b64_tr_b16 v[214:215], v157 offset:0x1c00
	s_waitcnt lgkmcnt(0)
	s_nop 0
	v_mfma_f32_32x32x16_bf16 v[16:31], v[66:69], v[200:203], v[16:31]
	ds_read_b64_tr_b16 v[200:201], v157 offset:0x200
	ds_read_b64_tr_b16 v[202:203], v157 offset:0x600
	v_mfma_f32_32x32x16_bf16 v[16:31], v[70:73], v[204:207], v[16:31]
	ds_read_b64_tr_b16 v[204:205], v157 offset:0xa00
	ds_read_b64_tr_b16 v[206:207], v157 offset:0xe00
	v_mfma_f32_32x32x16_bf16 v[16:31], v[74:77], v[208:211], v[16:31]
	ds_read_b64_tr_b16 v[208:209], v157 offset:0x1200
	ds_read_b64_tr_b16 v[210:211], v157 offset:0x1600
	v_mfma_f32_32x32x16_bf16 v[16:31], v[182:185], v[212:215], v[16:31]
	ds_read_b64_tr_b16 v[212:213], v157 offset:0x1a00
	ds_read_b64_tr_b16 v[214:215], v157 offset:0x1e00
	s_waitcnt lgkmcnt(0)
	v_mfma_f32_32x32x16_bf16 v[0:15], v[66:69], v[200:203], v[0:15]
	v_max_f32_e32 v66, v81, v81
	v_max_f32_e32 v67, v80, v80
	v_max_f32_e32 v66, v67, v66
	v_max3_f32 v66, v66, v82, v83
	v_max3_f32 v66, v66, v84, v85
	v_max3_f32 v66, v66, v86, v87
	v_max3_f32 v66, v66, v88, v89
	v_mfma_f32_32x32x16_bf16 v[0:15], v[70:73], v[204:207], v[0:15]
	v_max3_f32 v66, v66, v90, v91
	v_max3_f32 v66, v66, v92, v93
	v_max3_f32 v66, v66, v94, v95
	v_max3_f32 v66, v66, v48, v49
	v_max3_f32 v66, v66, v50, v51
	v_max3_f32 v66, v66, v52, v53
	v_max3_f32 v66, v66, v54, v55
	v_mfma_f32_32x32x16_bf16 v[0:15], v[74:77], v[208:211], v[0:15]
	v_max3_f32 v66, v66, v56, v57
	v_max3_f32 v66, v66, v58, v59
	v_max3_f32 v66, v66, v60, v61
	v_max3_f32 v66, v66, v62, v63
	v_mov_b32_e32 v67, v66
	s_nop 1
	v_permlane32_swap_b32_e32 v66, v67
	v_mfma_f32_32x32x16_bf16 v[0:15], v[182:185], v[212:215], v[0:15]
	v_max_f32_e32 v67, v67, v67
	v_max_f32_e32 v66, v66, v66
	v_max_f32_e32 v67, v66, v67
	v_cmp_ge_f32_e32 vcc, s76, v67
	s_cmp_eq_u64 vcc, exec
	v_mov_b32_e32 v66, 1.0
	s_cbranch_scc0 .LBB0_728
.LBB0_721:
	s_waitcnt vmcnt(3)
	ds_write_b128 v173, v[136:139] offset:32768
	ds_write_b128 v174, v[140:143] offset:32768
	s_waitcnt lgkmcnt(0)
	s_barrier
	v_cmp_gt_f32_e32 vcc, 1.0, v66
	ds_write_b128 v176, v[132:135] offset:8192
	s_cbranch_vccz .LBB0_725
	s_and_saveexec_b64 s[2:3], s[40:41]
	ds_write_b32 v164, v66 offset:49280
	s_or_b64 exec, exec, s[2:3]
	s_waitcnt lgkmcnt(0)
	v_add_u32_e32 v67, v163, v188
	ds_read_b128 v[68:71], v67 offset:49376
	ds_read_b128 v[72:75], v67 offset:49344
	ds_read_b128 v[76:79], v67 offset:49312
	ds_read_b128 v[132:135], v67 offset:49280
	s_waitcnt lgkmcnt(3)
	v_pk_mul_f32 v[28:29], v[28:29], v[68:69]
	s_waitcnt lgkmcnt(2)
	v_pk_mul_f32 v[24:25], v[24:25], v[72:73]
	s_waitcnt lgkmcnt(1)
	v_pk_mul_f32 v[20:21], v[20:21], v[76:77]
	v_pk_mul_f32 v[30:31], v[30:31], v[70:71]
	v_pk_mul_f32 v[26:27], v[26:27], v[74:75]
	v_pk_mul_f32 v[22:23], v[22:23], v[78:79]
	s_waitcnt lgkmcnt(0)
	v_pk_mul_f32 v[18:19], v[18:19], v[134:135]
	v_pk_mul_f32 v[16:17], v[16:17], v[132:133]
	v_pk_mul_f32 v[12:13], v[12:13], v[68:69]
	v_pk_mul_f32 v[8:9], v[8:9], v[72:73]
	v_pk_mul_f32 v[4:5], v[4:5], v[76:77]
	v_pk_mul_f32 v[14:15], v[14:15], v[70:71]
	v_pk_mul_f32 v[10:11], v[10:11], v[74:75]
	v_pk_mul_f32 v[6:7], v[6:7], v[78:79]
	v_pk_mul_f32 v[2:3], v[2:3], v[134:135]
	v_pk_mul_f32 v[0:1], v[0:1], v[132:133]
.LBB0_725:
	v_exp_f32_e32 v183, v80
	v_exp_f32_e32 v185, v81
	v_exp_f32_e32 v182, v82
	v_exp_f32_e32 v184, v83
	v_exp_f32_e32 v141, v84
	v_exp_f32_e32 v143, v85
	v_exp_f32_e32 v140, v86
	v_exp_f32_e32 v142, v87
	v_exp_f32_e32 v137, v88
	v_exp_f32_e32 v139, v89
	v_exp_f32_e32 v135, v90
	v_exp_f32_e32 v138, v91
	v_exp_f32_e32 v133, v92
	v_exp_f32_e32 v136, v93
	v_exp_f32_e32 v132, v94
	v_exp_f32_e32 v134, v95
	v_add_f32_e32 v67, v179, v180
	v_fmac_f32_e32 v67, v178, v147
	v_add_f32_e32 v147, v64, v65
	s_add_i32 s2, s59, 2
	v_fmac_f32_e32 v147, v67, v181
	v_lshl_add_u64 v[154:155], v[154:155], 0, s[30:31]
	s_cmp_ge_u32 s2, s20
	v_lshl_add_u64 v[158:159], v[158:159], 0, s[28:29]
	s_waitcnt lgkmcnt(0)
	s_cbranch_scc1 .LBB0_729
	s_mov_b32 s59, s2
	v_mov_b32_e32 v178, v66
	s_branch .LBB0_715

.LBB0_734:
	s_waitcnt vmcnt(3)
	ds_write_b128 v173, v[124:127] offset:16384
	ds_write_b128 v174, v[128:131] offset:16384
	s_waitcnt lgkmcnt(0)
	s_barrier
	v_cmp_gt_f32_e32 vcc, 1.0, v186
	ds_write_b128 v176, v[120:123]
	s_cbranch_vccz .LBB0_738
	s_and_saveexec_b64 s[0:1], s[40:41]
	ds_write_b32 v164, v186 offset:49280
	s_or_b64 exec, exec, s[0:1]
	s_waitcnt lgkmcnt(0)
	v_add_u32_e32 v60, v163, v188
	ds_read_b128 v[48:51], v60 offset:49376
	ds_read_b128 v[52:55], v60 offset:49344
	ds_read_b128 v[56:59], v60 offset:49312
	ds_read_b128 v[60:63], v60 offset:49280
	s_waitcnt lgkmcnt(3)
	v_pk_mul_f32 v[28:29], v[28:29], v[48:49]
	s_waitcnt lgkmcnt(2)
	v_pk_mul_f32 v[24:25], v[24:25], v[52:53]
	s_waitcnt lgkmcnt(1)
	v_pk_mul_f32 v[20:21], v[20:21], v[56:57]
	v_pk_mul_f32 v[30:31], v[30:31], v[50:51]
	v_pk_mul_f32 v[26:27], v[26:27], v[54:55]
	v_pk_mul_f32 v[22:23], v[22:23], v[58:59]
	s_waitcnt lgkmcnt(0)
	v_pk_mul_f32 v[18:19], v[18:19], v[62:63]
	v_pk_mul_f32 v[16:17], v[16:17], v[60:61]
	v_pk_mul_f32 v[12:13], v[12:13], v[48:49]
	v_pk_mul_f32 v[8:9], v[8:9], v[52:53]
	v_pk_mul_f32 v[4:5], v[4:5], v[56:57]
	v_pk_mul_f32 v[14:15], v[14:15], v[50:51]
	v_pk_mul_f32 v[10:11], v[10:11], v[54:55]
	v_pk_mul_f32 v[6:7], v[6:7], v[58:59]
	v_pk_mul_f32 v[2:3], v[2:3], v[62:63]
	v_pk_mul_f32 v[0:1], v[0:1], v[60:61]
.LBB0_738:
	v_exp_f32_e32 v181, v82
	v_exp_f32_e32 v129, v84
	v_exp_f32_e32 v131, v85
	v_exp_f32_e32 v128, v86
	v_exp_f32_e32 v130, v87
	v_exp_f32_e32 v125, v88
	v_exp_f32_e32 v127, v89
	v_exp_f32_e32 v123, v90
	v_exp_f32_e32 v126, v91
	v_exp_f32_e32 v121, v92
	v_exp_f32_e32 v124, v93
	v_exp_f32_e32 v120, v94
	v_exp_f32_e32 v122, v95
	v_exp_f32_e32 v182, v80
	v_exp_f32_e32 v184, v81
	v_exp_f32_e32 v183, v83
	s_add_i32 s0, s2, 1
	s_waitcnt lgkmcnt(0)
	ds_read_b128 v[200:203], v166 offset:16384
	ds_read_b128 v[204:207], v166 offset:24576
	s_cmp_le_i32 s0, s21
	s_cselect_b64 vcc, -1, 0
	v_cndmask_b32_e32 v63, v229, v47, vcc
	v_cndmask_b32_e32 v62, v229, v46, vcc
	v_cndmask_b32_e32 v61, v229, v45, vcc
	v_cndmask_b32_e32 v60, v229, v44, vcc
	v_cndmask_b32_e32 v59, v229, v43, vcc
	v_cndmask_b32_e32 v58, v229, v42, vcc
	v_cndmask_b32_e32 v57, v229, v41, vcc
	v_cndmask_b32_e32 v56, v229, v40, vcc
	v_cndmask_b32_e32 v55, v229, v39, vcc
	v_cndmask_b32_e32 v54, v229, v38, vcc
	v_cndmask_b32_e32 v53, v229, v37, vcc
	v_cndmask_b32_e32 v52, v229, v36, vcc
	v_cndmask_b32_e32 v51, v229, v35, vcc
	v_cndmask_b32_e32 v50, v229, v34, vcc
	v_cndmask_b32_e32 v49, v229, v33, vcc
	v_cndmask_b32_e32 v48, v229, v32, vcc
	v_exp_f32_e32 v185, v64
	v_add_f32_e32 v64, 0, v182
	s_waitcnt lgkmcnt(1)
	v_mfma_f32_32x32x16_bf16 v[80:95], v[200:203], v[116:119], v[48:63]
	v_add_f32_e32 v64, v184, v64
	v_add_f32_e32 v64, v181, v64
	v_add_f32_e32 v64, v183, v64
	v_add_f32_e32 v64, v129, v64
	v_add_f32_e32 v64, v131, v64
	v_add_f32_e32 v64, v128, v64
	v_add_f32_e32 v64, v130, v64
	s_waitcnt lgkmcnt(0)
	v_mfma_f32_32x32x16_bf16 v[48:63], v[204:207], v[116:119], v[48:63]
	ds_read_b128 v[200:203], v167 offset:16384
	ds_read_b128 v[204:207], v167 offset:24576
	v_add_f32_e32 v64, v125, v64
	v_add_f32_e32 v64, v127, v64
	v_add_f32_e32 v64, v123, v64
	v_add_f32_e32 v64, v126, v64
	v_add_f32_e32 v64, v121, v64
	v_exp_f32_e32 v187, v65
	s_waitcnt lgkmcnt(1)
	v_mfma_f32_32x32x16_bf16 v[80:95], v[200:203], v[112:115], v[80:95]
	v_add_f32_e32 v64, v124, v64
	v_exp_f32_e32 v196, v66
	v_add_f32_e32 v64, v120, v64
	v_exp_f32_e32 v197, v67
	v_add_f32_e32 v64, v122, v64
	v_add_f32_e32 v64, v185, v64
	v_add_f32_e32 v64, v187, v64
	s_waitcnt lgkmcnt(0)
	v_mfma_f32_32x32x16_bf16 v[48:63], v[204:207], v[112:115], v[48:63]
	ds_read_b128 v[200:203], v169 offset:16384
	ds_read_b128 v[204:207], v169 offset:24576
	v_add_f32_e32 v64, v196, v64
	v_add_f32_e32 v64, v197, v64
	v_exp_f32_e32 v208, v76
	v_exp_f32_e32 v209, v77
	v_exp_f32_e32 v78, v78
	v_exp_f32_e32 v79, v79
	s_waitcnt lgkmcnt(1)
	v_mfma_f32_32x32x16_bf16 v[80:95], v[200:203], v[108:111], v[80:95]
	s_waitcnt lgkmcnt(0)
	v_mfma_f32_32x32x16_bf16 v[48:63], v[204:207], v[108:111], v[48:63]
	ds_read_b128 v[200:203], v170 offset:16384
	ds_read_b128 v[204:207], v170 offset:24576
	s_waitcnt lgkmcnt(1)
	v_mfma_f32_32x32x16_bf16 v[80:95], v[200:203], v[104:107], v[80:95]
	s_waitcnt lgkmcnt(0)
	v_mfma_f32_32x32x16_bf16 v[48:63], v[204:207], v[104:107], v[48:63]
	ds_read_b128 v[200:203], v168 offset:16384
	ds_read_b128 v[204:207], v168 offset:24576
	s_waitcnt lgkmcnt(1)
	v_mfma_f32_32x32x16_bf16 v[80:95], v[200:203], v[100:103], v[80:95]
	s_waitcnt lgkmcnt(0)
	v_mfma_f32_32x32x16_bf16 v[48:63], v[204:207], v[100:103], v[48:63]
	ds_read_b128 v[200:203], v171 offset:16384
	ds_read_b128 v[204:207], v171 offset:24576
	v_cvt_pk_bf16_f32 v66, v182, v184
	v_cvt_pk_bf16_f32 v67, v181, v183
	s_waitcnt lgkmcnt(1)
	v_mfma_f32_32x32x16_bf16 v[80:95], v[200:203], v[96:99], v[80:95]
	v_exp_f32_e32 v200, v68
	v_exp_f32_e32 v201, v69
	v_exp_f32_e32 v202, v70
	v_exp_f32_e32 v203, v71
	v_add_f32_e32 v64, v200, v64
	v_add_f32_e32 v64, v201, v64
	v_add_f32_e32 v64, v202, v64
	s_waitcnt lgkmcnt(0)
	v_mfma_f32_32x32x16_bf16 v[48:63], v[204:207], v[96:99], v[48:63]
	v_exp_f32_e32 v204, v72
	v_exp_f32_e32 v205, v73
	v_exp_f32_e32 v206, v74
	v_exp_f32_e32 v207, v75
	v_add_f32_e32 v64, v203, v64
	v_add_f32_e32 v64, v204, v64
	v_add_f32_e32 v64, v205, v64
	v_add_f32_e32 v64, v206, v64
	v_add_f32_e32 v64, v207, v64
	v_add_f32_e32 v64, v208, v64
	v_add_f32_e32 v64, v209, v64
	v_add_f32_e32 v64, v78, v64
	v_add_f32_e32 v64, v79, v64
	v_mov_b32_e32 v65, v64
	v_cvt_pk_bf16_f32 v68, v129, v131
	s_nop 1
	v_permlane32_swap_b32_e32 v64, v65
	v_cvt_pk_bf16_f32 v69, v128, v130
	v_permlane32_swap_b32_e32 v66, v68
	v_cvt_pk_bf16_f32 v70, v125, v127
	v_cvt_pk_bf16_f32 v71, v123, v126
	v_cvt_pk_bf16_f32 v72, v121, v124
	v_cvt_pk_bf16_f32 v73, v120, v122
	v_cvt_pk_bf16_f32 v74, v185, v187
	v_cvt_pk_bf16_f32 v75, v196, v197
	v_cvt_pk_bf16_f32 v76, v200, v201
	v_cvt_pk_bf16_f32 v77, v202, v203
	v_cvt_pk_bf16_f32 v182, v204, v205
	v_cvt_pk_bf16_f32 v183, v206, v207
	v_cvt_pk_bf16_f32 v184, v208, v209
	v_cvt_pk_bf16_f32 v185, v78, v79
	v_permlane32_swap_b32_e32 v67, v69
	v_permlane32_swap_b32_e32 v70, v72
	v_permlane32_swap_b32_e32 v71, v73
	v_permlane32_swap_b32_e32 v74, v76
	v_permlane32_swap_b32_e32 v75, v77
	v_permlane32_swap_b32_e32 v182, v184
	v_permlane32_swap_b32_e32 v183, v185
	s_add_i32 s60, s2, 3
	s_min_u32 s0, s60, s57
	s_lshl_b32 s0, s0, 6
	v_add_u32_e32 v78, s0, v148
	v_ashrrev_i32_e32 v79, 31, v78
	v_lshlrev_b64 v[78:79], 7, v[78:79]
	v_lshl_add_u64 v[78:79], v[152:153], 0, v[78:79]
	global_load_dwordx4 v[120:123], v[78:79], off
	v_add_u32_e32 v78, s0, v146
	v_add_u32_e32 v124, s0, v150
	v_ashrrev_i32_e32 v79, 31, v78
	v_ashrrev_i32_e32 v125, 31, v124
	v_lshlrev_b64 v[78:79], v172, v[78:79]
	v_lshlrev_b64 v[124:125], v172, v[124:125]
	v_lshl_add_u64 v[78:79], v[78:79], 1, v[144:145]
	v_lshl_add_u64 v[128:129], v[124:125], 1, v[144:145]
	global_load_dwordx4 v[124:127], v[78:79], off
	s_nop 0
	global_load_dwordx4 v[128:131], v[128:129], off
	ds_read_b64_tr_b16 v[200:201], v155 offset:0
	ds_read_b64_tr_b16 v[202:203], v155 offset:0x400
	ds_read_b64_tr_b16 v[204:205], v155 offset:0x800
	ds_read_b64_tr_b16 v[206:207], v155 offset:0xc00
	ds_read_b64_tr_b16 v[208:209], v155 offset:0x1000
	ds_read_b64_tr_b16 v[210:211], v155 offset:0x1400
	ds_read_b64_tr_b16 v[212:213], v155 offset:0x1800
	ds_read_b64_tr_b16 v[214:215], v155 offset:0x1c00
	s_waitcnt lgkmcnt(0)
	s_nop 0
	v_mfma_f32_32x32x16_bf16 v[16:31], v[66:69], v[200:203], v[16:31]
	ds_read_b64_tr_b16 v[200:201], v155 offset:0x200
	ds_read_b64_tr_b16 v[202:203], v155 offset:0x600
	v_mfma_f32_32x32x16_bf16 v[16:31], v[70:73], v[204:207], v[16:31]
	ds_read_b64_tr_b16 v[204:205], v155 offset:0xa00
	ds_read_b64_tr_b16 v[206:207], v155 offset:0xe00
	v_mfma_f32_32x32x16_bf16 v[16:31], v[74:77], v[208:211], v[16:31]
	ds_read_b64_tr_b16 v[208:209], v155 offset:0x1200
	ds_read_b64_tr_b16 v[210:211], v155 offset:0x1600
	v_mfma_f32_32x32x16_bf16 v[16:31], v[182:185], v[212:215], v[16:31]
	ds_read_b64_tr_b16 v[212:213], v155 offset:0x1a00
	ds_read_b64_tr_b16 v[214:215], v155 offset:0x1e00
	s_waitcnt lgkmcnt(0)
	v_mfma_f32_32x32x16_bf16 v[0:15], v[66:69], v[200:203], v[0:15]
	v_max_f32_e32 v66, v81, v81
	v_max_f32_e32 v67, v80, v80
	v_max_f32_e32 v66, v67, v66
	v_max3_f32 v66, v66, v82, v83
	v_max3_f32 v66, v66, v84, v85
	v_max3_f32 v66, v66, v86, v87
	v_max3_f32 v66, v66, v88, v89
	v_mfma_f32_32x32x16_bf16 v[0:15], v[70:73], v[204:207], v[0:15]
	v_max3_f32 v66, v66, v90, v91
	v_max3_f32 v66, v66, v92, v93
	v_max3_f32 v66, v66, v94, v95
	v_max3_f32 v66, v66, v48, v49
	v_max3_f32 v66, v66, v50, v51
	v_max3_f32 v66, v66, v52, v53
	v_max3_f32 v66, v66, v54, v55
	v_mfma_f32_32x32x16_bf16 v[0:15], v[74:77], v[208:211], v[0:15]
	v_max3_f32 v66, v66, v56, v57
	v_max3_f32 v66, v66, v58, v59
	v_max3_f32 v66, v66, v60, v61
	v_max3_f32 v66, v66, v62, v63
	v_mov_b32_e32 v67, v66
	s_nop 1
	v_permlane32_swap_b32_e32 v66, v67
	v_mfma_f32_32x32x16_bf16 v[0:15], v[182:185], v[212:215], v[0:15]
	v_max_f32_e32 v67, v67, v67
	v_max_f32_e32 v66, v66, v66
	v_max_f32_e32 v66, v66, v67
	v_cmp_ge_f32_e32 vcc, s76, v66
	s_cmp_eq_u64 vcc, exec
	v_mov_b32_e32 v181, 1.0
	s_cbranch_scc0 .LBB0_746
.LBB0_739:
	s_waitcnt vmcnt(3)
	ds_write_b128 v173, v[136:139] offset:32768
	ds_write_b128 v174, v[140:143] offset:32768
	s_waitcnt lgkmcnt(0)
	s_barrier
	v_cmp_gt_f32_e32 vcc, 1.0, v181
	ds_write_b128 v176, v[132:135] offset:8192
	s_cbranch_vccz .LBB0_743
	s_and_saveexec_b64 s[0:1], s[40:41]
	ds_write_b32 v164, v181 offset:49280
	s_or_b64 exec, exec, s[0:1]
	s_waitcnt lgkmcnt(0)
	v_add_u32_e32 v78, v163, v188
	ds_read_b128 v[66:69], v78 offset:49376
	ds_read_b128 v[70:73], v78 offset:49344
	ds_read_b128 v[74:77], v78 offset:49312
	ds_read_b128 v[132:135], v78 offset:49280
	s_waitcnt lgkmcnt(3)
	v_pk_mul_f32 v[28:29], v[28:29], v[66:67]
	s_waitcnt lgkmcnt(2)
	v_pk_mul_f32 v[24:25], v[24:25], v[70:71]
	s_waitcnt lgkmcnt(1)
	v_pk_mul_f32 v[20:21], v[20:21], v[74:75]
	v_pk_mul_f32 v[30:31], v[30:31], v[68:69]
	v_pk_mul_f32 v[26:27], v[26:27], v[72:73]
	v_pk_mul_f32 v[22:23], v[22:23], v[76:77]
	s_waitcnt lgkmcnt(0)
	v_pk_mul_f32 v[18:19], v[18:19], v[134:135]
	v_pk_mul_f32 v[16:17], v[16:17], v[132:133]
	v_pk_mul_f32 v[12:13], v[12:13], v[66:67]
	v_pk_mul_f32 v[8:9], v[8:9], v[70:71]
	v_pk_mul_f32 v[4:5], v[4:5], v[74:75]
	v_pk_mul_f32 v[14:15], v[14:15], v[68:69]
	v_pk_mul_f32 v[10:11], v[10:11], v[72:73]
	v_pk_mul_f32 v[6:7], v[6:7], v[76:77]
	v_pk_mul_f32 v[2:3], v[2:3], v[134:135]
	v_pk_mul_f32 v[0:1], v[0:1], v[132:133]
.LBB0_743:
	v_exp_f32_e32 v183, v80
	v_exp_f32_e32 v185, v81
	v_exp_f32_e32 v182, v82
	v_exp_f32_e32 v184, v83
	v_exp_f32_e32 v141, v84
	v_exp_f32_e32 v143, v85
	v_exp_f32_e32 v140, v86
	v_exp_f32_e32 v142, v87
	v_exp_f32_e32 v137, v88
	v_exp_f32_e32 v139, v89
	v_exp_f32_e32 v135, v90
	v_exp_f32_e32 v138, v91
	v_exp_f32_e32 v133, v92
	v_exp_f32_e32 v136, v93
	v_exp_f32_e32 v132, v94
	v_exp_f32_e32 v134, v95
	v_add_f32_e32 v66, v179, v180
	v_fmac_f32_e32 v66, v178, v147
	v_add_f32_e32 v147, v64, v65
	s_add_i32 s2, s2, 2
	v_fmac_f32_e32 v147, v66, v186
	v_lshl_add_u64 v[156:157], v[156:157], 0, s[30:31]
	v_lshl_add_u64 v[158:159], v[158:159], 0, s[30:31]
	s_cmp_lt_u32 s60, s20
	v_lshl_add_u64 v[160:161], v[160:161], 0, s[28:29]
	s_waitcnt lgkmcnt(0)
	s_cbranch_scc0 .LBB0_748
	v_mov_b32_e32 v178, v181
	s_branch .LBB0_733
